# v7 + attention: K-tile LDS writes moved before the first per-tile barrier (only V writes remain between the two barriers)
# speedup vs baseline: 1.0054x; 1.0031x over previous
.LBB0_1056:
	v_max_f32_e32 v151, v67, v67
	v_max_f32_e32 v152, v66, v66
	v_max_f32_e32 v151, v152, v151
	v_max3_f32 v150, v82, v83, v84
	v_max3_f32 v151, v151, v68, v72
	v_max3_f32 v150, v150, v88, v89
	v_max3_f32 v151, v151, v73, v74
	v_max3_f32 v150, v150, v90, v91
	v_max3_f32 v151, v151, v75, v76
	v_max3_f32 v150, v150, v92, v93
	v_max3_f32 v151, v151, v77, v78
	v_max3_f32 v150, v150, v94, v95
	v_max3_f32 v151, v151, v79, v80
	v_max3_f32 v153, v69, v70, v71
	v_max3_f32 v150, v150, v96, v97
	v_max3_f32 v152, v85, v86, v87
	v_max3_f32 v151, v151, v81, v153
	v_max3_f32 v150, v150, v152, v151
	v_mov_b32_e32 v151, v150
	s_nop 1
	v_permlane32_swap_b32_e32 v150, v151
	v_max_f32_e32 v151, v151, v151
	v_max_f32_e32 v150, v150, v150
	v_max_f32_e32 v150, v150, v151
	v_max_f32_e32 v152, v162, v162
	v_sub_f32_e32 v151, v150, v162
	v_max_f32_e32 v150, v152, v150
	v_sub_f32_e32 v152, v162, v150
	v_mul_f32_e32 v152, 0x3dd53b94, v152
	v_mul_f32_e32 v151, 0x3d93cd3a, v151
	v_exp_f32_e32 v152, v152
	v_cmp_ge_f32_e32 vcc, s3, v151
	s_cmp_eq_u64 vcc, exec
	s_cselect_b64 s[6:7], -1, 0
	s_waitcnt vmcnt(0)
	ds_write_b128 v204, v[138:141] offset:32768
	ds_write_b128 v204, v[142:145] offset:40960
	ds_write_b128 v205, v[146:149] offset:49152
	s_barrier
	s_waitcnt vmcnt(0)
	v_cndmask_b32_e64 v220, v152, 1.0, s[6:7]
	v_cmp_gt_f32_e32 vcc, 1.0, v220
	ds_write_b128 v202, v[130:133]
	ds_write_b128 v203, v[134:137]
	s_cbranch_vccz .LBB0_1060
	s_and_saveexec_b64 s[0:1], s[4:5]
	ds_write_b32 v199, v220 offset:128
	s_or_b64 exec, exec, s[0:1]
	s_waitcnt lgkmcnt(0)
	ds_read_b128 v[152:155], v198 offset:224
	ds_read_b128 v[156:159], v198 offset:192
	ds_read_b128 v[222:225], v198 offset:160
	ds_read_b128 v[226:229], v198 offset:128
	s_waitcnt lgkmcnt(3)
	v_pk_mul_f32 v[64:65], v[64:65], v[154:155]
	s_waitcnt lgkmcnt(2)
	v_pk_mul_f32 v[60:61], v[60:61], v[158:159]
	s_waitcnt lgkmcnt(1)
	v_pk_mul_f32 v[56:57], v[56:57], v[224:225]
	s_waitcnt lgkmcnt(0)
	v_pk_mul_f32 v[52:53], v[52:53], v[228:229]
	v_pk_mul_f32 v[62:63], v[62:63], v[152:153]
	v_pk_mul_f32 v[58:59], v[58:59], v[156:157]
	v_pk_mul_f32 v[54:55], v[54:55], v[222:223]
	v_pk_mul_f32 v[50:51], v[50:51], v[226:227]
	v_pk_mul_f32 v[48:49], v[48:49], v[154:155]
	v_pk_mul_f32 v[44:45], v[44:45], v[158:159]
	v_pk_mul_f32 v[40:41], v[40:41], v[224:225]
	v_pk_mul_f32 v[36:37], v[36:37], v[228:229]
	v_pk_mul_f32 v[46:47], v[46:47], v[152:153]
	v_pk_mul_f32 v[42:43], v[42:43], v[156:157]
	v_pk_mul_f32 v[38:39], v[38:39], v[222:223]
	v_pk_mul_f32 v[34:35], v[34:35], v[226:227]
	v_pk_mul_f32 v[32:33], v[32:33], v[154:155]
	v_pk_mul_f32 v[28:29], v[28:29], v[158:159]
	v_pk_mul_f32 v[24:25], v[24:25], v[224:225]
	v_pk_mul_f32 v[20:21], v[20:21], v[228:229]
	v_pk_mul_f32 v[30:31], v[30:31], v[152:153]
	v_pk_mul_f32 v[26:27], v[26:27], v[156:157]
	v_pk_mul_f32 v[22:23], v[22:23], v[222:223]
	v_pk_mul_f32 v[18:19], v[18:19], v[226:227]
	v_pk_mul_f32 v[16:17], v[16:17], v[154:155]
	v_pk_mul_f32 v[12:13], v[12:13], v[158:159]
	v_pk_mul_f32 v[8:9], v[8:9], v[224:225]
	v_pk_mul_f32 v[4:5], v[4:5], v[228:229]
	v_pk_mul_f32 v[14:15], v[14:15], v[152:153]
	v_pk_mul_f32 v[10:11], v[10:11], v[156:157]
	v_pk_mul_f32 v[6:7], v[6:7], v[222:223]
	v_pk_mul_f32 v[2:3], v[2:3], v[226:227]

.LBB0_1064:
	v_max_f32_e32 v151, v67, v67
	v_max_f32_e32 v152, v66, v66
	v_max_f32_e32 v151, v152, v151
	v_max3_f32 v150, v82, v83, v84
	v_max3_f32 v151, v151, v68, v72
	v_max3_f32 v150, v150, v88, v89
	v_max3_f32 v151, v151, v73, v74
	v_max3_f32 v150, v150, v90, v91
	v_max3_f32 v151, v151, v75, v76
	v_max3_f32 v150, v150, v92, v93
	v_max3_f32 v151, v151, v77, v78
	v_max3_f32 v150, v150, v94, v95
	v_max3_f32 v151, v151, v79, v80
	v_max3_f32 v153, v69, v70, v71
	v_max3_f32 v150, v150, v96, v97
	v_max3_f32 v152, v85, v86, v87
	v_max3_f32 v151, v151, v81, v153
	v_max3_f32 v150, v150, v152, v151
	v_mov_b32_e32 v151, v150
	s_nop 1
	v_permlane32_swap_b32_e32 v150, v151
	v_max_f32_e32 v151, v151, v151
	v_max_f32_e32 v150, v150, v150
	v_max_f32_e32 v150, v150, v151
	v_sub_f32_e32 v151, v150, v221
	v_mul_f32_e32 v151, 0x3d93cd3a, v151
	v_cmp_ge_f32_e32 vcc, s3, v151
	s_cmp_eq_u64 vcc, exec
	s_cselect_b64 s[6:7], -1, 0
	s_andn2_b64 vcc, exec, s[76:77]
	s_cbranch_vccnz .Lattn_skipk
	s_waitcnt vmcnt(0)
	ds_write_b128 v216, v[138:141]
	ds_write_b128 v216, v[142:145] offset:8192
	ds_write_b128 v217, v[146:149]
.Lattn_skipk:
	s_barrier
	s_cbranch_vccnz .LBB0_1066
	s_waitcnt vmcnt(0)
	ds_write_b128 v202, v[130:133] offset:16384
	ds_write_b128 v203, v[134:137] offset:16384
